# adds: layer-1 WDN transposes moved into the idle half-round of the layer-1 up-GEMM
# speedup vs baseline: 1.0180x; 1.0119x over previous
.LBB0_130:
	s_or_b64 exec, exec, s[0:1]
	s_load_dwordx2 s[0:1], s[92:93], 0x58
	s_load_dwordx2 s[2:3], s[92:93], 0xb8
	s_load_dwordx2 s[4:5], s[92:93], 0xc0
	s_load_dwordx2 s[6:7], s[92:93], 0xc8
	s_load_dwordx2 s[8:9], s[92:93], 0xd0
	s_load_dwordx2 s[10:11], s[92:93], 0xe8
	v_and_b32_e32 v74, 63, v154
	v_lshrrev_b32_e32 v75, 6, v154
	v_mul_u32_u24_e32 v75, 0x2100, v75
	v_lshrrev_b32_e32 v3, 5, v74
	v_and_b32_e32 v4, 31, v74
	v_lshlrev_b32_e32 v4, 2, v4
	v_lshrrev_b32_e32 v5, 3, v74
	v_and_b32_e32 v6, 7, v74
	v_mul_u32_u24_e32 v2, 264, v6
	v_add_u32_e32 v2, v2, v5
	v_lshl_add_u32 v2, v2, 2, v75
	v_lshlrev_b32_e32 v6, 4, v6
	v_mul_u32_u24_e32 v1, 132, v5
	v_add3_u32 v1, v1, v6, v75
	v_readfirstlane_b32 s13, v154
	s_lshr_b32 s13, s13, 6
	s_lshl_b32 s26, s96, 3
	s_add_u32 s13, s13, s26
	s_mov_b32 s12, s13
	s_waitcnt lgkmcnt(0)
	s_cmp_ge_u32 s12, 44544
	s_cbranch_scc1 .Ltra_done
	s_cmp_ge_u32 s12, 33280
	s_cselect_b32 s41, 1, 0
	s_cselect_b32 s26, 33280, 0
	s_sub_u32 s42, s12, s26
	s_cmp_ge_u32 s42, 12288
	s_cbranch_scc1 .Ltra_m2
	s_mul_i32 s43, s42, 43691
	s_lshr_b32 s43, s43, 24
	s_mul_i32 s26, s43, 384
	s_sub_u32 s44, s42, s26
	s_mov_b32 s14, s0
	s_mov_b32 s15, s1
	s_mov_b32 s36, 0xc000
	s_mov_b32 s37, 0x6000000
	s_mov_b32 s38, 0x0
	s_mov_b32 s39, 0x3000000
	s_mov_b32 s40, 0x1000
	s_branch .Ltra_dec_done1

.Ltra_loop:
	s_add_u32 s12, s12, 2048
	s_cmp_lt_u32 s12, 44544
	s_cselect_b32 s24, 1, 0
	s_cbranch_scc0 .Ltra_nonext8
	s_cmp_ge_u32 s12, 33280
	s_cselect_b32 s41, 1, 0
	s_cselect_b32 s26, 33280, 0
	s_sub_u32 s42, s12, s26
	s_cmp_ge_u32 s42, 12288
	s_cbranch_scc1 .Ltra_m11
	s_mul_i32 s43, s42, 43691
	s_lshr_b32 s43, s43, 24
	s_mul_i32 s26, s43, 384
	s_sub_u32 s44, s42, s26
	s_mov_b32 s16, s0
	s_mov_b32 s17, s1
	s_mov_b32 s36, 0xc000
	s_mov_b32 s37, 0x6000000
	s_mov_b32 s38, 0x0
	s_mov_b32 s39, 0x3000000
	s_mov_b32 s40, 0x1000
	s_branch .Ltra_dec_done10

.Ltra_after9:
	ds_write_b32 v1, v10 offset:0
	ds_write_b32 v1, v11 offset:4
	ds_write_b32 v1, v12 offset:8
	ds_write_b32 v1, v13 offset:12
	ds_write_b32 v1, v14 offset:1056
	ds_write_b32 v1, v15 offset:1060
	ds_write_b32 v1, v16 offset:1064
	ds_write_b32 v1, v17 offset:1068
	ds_write_b32 v1, v18 offset:2112
	ds_write_b32 v1, v19 offset:2116
	ds_write_b32 v1, v20 offset:2120
	ds_write_b32 v1, v21 offset:2124
	ds_write_b32 v1, v22 offset:3168
	ds_write_b32 v1, v23 offset:3172
	ds_write_b32 v1, v24 offset:3176
	ds_write_b32 v1, v25 offset:3180
	ds_write_b32 v1, v26 offset:4224
	ds_write_b32 v1, v27 offset:4228
	ds_write_b32 v1, v28 offset:4232
	ds_write_b32 v1, v29 offset:4236
	ds_write_b32 v1, v30 offset:5280
	ds_write_b32 v1, v31 offset:5284
	ds_write_b32 v1, v32 offset:5288
	ds_write_b32 v1, v33 offset:5292
	ds_write_b32 v1, v34 offset:6336
	ds_write_b32 v1, v35 offset:6340
	ds_write_b32 v1, v36 offset:6344
	ds_write_b32 v1, v37 offset:6348
	ds_write_b32 v1, v38 offset:7392
	ds_write_b32 v1, v39 offset:7396
	ds_write_b32 v1, v40 offset:7400
	ds_write_b32 v1, v41 offset:7404
	v_mad_u32_u24 v9, v5, s22, v6
	s_lshl_b32 s46, s22, 3
	s_waitcnt lgkmcnt(0)
	ds_read_b32 v74, v2 offset:0
	ds_read_b32 v75, v2 offset:132
	ds_read_b32 v76, v2 offset:264
	ds_read_b32 v77, v2 offset:396
	ds_read_b32 v78, v2 offset:528
	ds_read_b32 v79, v2 offset:660
	ds_read_b32 v80, v2 offset:792
	ds_read_b32 v81, v2 offset:924
	ds_read_b32 v82, v2 offset:32
	ds_read_b32 v83, v2 offset:164
	ds_read_b32 v84, v2 offset:296
	ds_read_b32 v85, v2 offset:428
	ds_read_b32 v86, v2 offset:560
	ds_read_b32 v87, v2 offset:692
	ds_read_b32 v88, v2 offset:824
	ds_read_b32 v89, v2 offset:956
	s_waitcnt lgkmcnt(8)
	v_cvt_pk_bf16_f32 v106, v74, v75
	v_cvt_pk_bf16_f32 v107, v76, v77
	v_cvt_pk_bf16_f32 v108, v78, v79
	v_cvt_pk_bf16_f32 v109, v80, v81
	global_store_dwordx4 v9, v[106:109], s[18:19]
	s_add_u32 s18, s18, s46
	s_addc_u32 s19, s19, 0
	ds_read_b32 v90, v2 offset:64
	ds_read_b32 v91, v2 offset:196
	ds_read_b32 v92, v2 offset:328
	ds_read_b32 v93, v2 offset:460
	ds_read_b32 v94, v2 offset:592
	ds_read_b32 v95, v2 offset:724
	ds_read_b32 v96, v2 offset:856
	ds_read_b32 v97, v2 offset:988
	s_waitcnt lgkmcnt(8)
	v_cvt_pk_bf16_f32 v110, v82, v83
	v_cvt_pk_bf16_f32 v111, v84, v85
	v_cvt_pk_bf16_f32 v112, v86, v87
	v_cvt_pk_bf16_f32 v113, v88, v89
	global_store_dwordx4 v9, v[110:113], s[18:19]
	s_add_u32 s18, s18, s46
	s_addc_u32 s19, s19, 0
	ds_read_b32 v98, v2 offset:96
	ds_read_b32 v99, v2 offset:228
	ds_read_b32 v100, v2 offset:360
	ds_read_b32 v101, v2 offset:492
	ds_read_b32 v102, v2 offset:624
	ds_read_b32 v103, v2 offset:756
	ds_read_b32 v104, v2 offset:888
	ds_read_b32 v105, v2 offset:1020
	s_waitcnt lgkmcnt(8)
	v_cvt_pk_bf16_f32 v106, v90, v91
	v_cvt_pk_bf16_f32 v107, v92, v93
	v_cvt_pk_bf16_f32 v108, v94, v95
	v_cvt_pk_bf16_f32 v109, v96, v97
	global_store_dwordx4 v9, v[106:109], s[18:19]
	s_add_u32 s18, s18, s46
	s_addc_u32 s19, s19, 0
	s_waitcnt lgkmcnt(0)
	v_cvt_pk_bf16_f32 v110, v98, v99
	v_cvt_pk_bf16_f32 v111, v100, v101
	v_cvt_pk_bf16_f32 v112, v102, v103
	v_cvt_pk_bf16_f32 v113, v104, v105
	global_store_dwordx4 v9, v[110:113], s[18:19]
	s_cmp_eq_u32 s24, 0
	s_cbranch_scc1 .Ltra_done
	s_add_u32 s12, s12, 2048
	s_cmp_lt_u32 s12, 44544
	s_cselect_b32 s24, 1, 0
	s_cbranch_scc0 .Ltra_nonext17
	s_cmp_ge_u32 s12, 33280
	s_cselect_b32 s41, 1, 0
	s_cselect_b32 s26, 33280, 0
	s_sub_u32 s42, s12, s26
	s_cmp_ge_u32 s42, 12288
	s_cbranch_scc1 .Ltra_m20
	s_mul_i32 s43, s42, 43691
	s_lshr_b32 s43, s43, 24
	s_mul_i32 s26, s43, 384
	s_sub_u32 s44, s42, s26
	s_mov_b32 s14, s0
	s_mov_b32 s15, s1
	s_mov_b32 s36, 0xc000
	s_mov_b32 s37, 0x6000000
	s_mov_b32 s38, 0x0
	s_mov_b32 s39, 0x3000000
	s_mov_b32 s40, 0x1000
	s_branch .Ltra_dec_done19

.LBB0_1179:
	s_waitcnt vmcnt(0)
	s_barrier
	s_cmp_lt_u32 s96, 128
	s_cbranch_scc1 .LBB0_1180
	s_load_dwordx2 s[0:1], s[92:93], 0x58
	s_load_dwordx2 s[2:3], s[92:93], 0xb8
	s_load_dwordx2 s[4:5], s[92:93], 0xc0
	s_load_dwordx2 s[6:7], s[92:93], 0xc8
	s_load_dwordx2 s[8:9], s[92:93], 0xd0
	s_load_dwordx2 s[10:11], s[92:93], 0xe8
	v_and_b32_e32 v74, 63, v154
	v_lshrrev_b32_e32 v75, 6, v154
	v_mul_u32_u24_e32 v75, 0x2100, v75
	v_lshrrev_b32_e32 v3, 5, v74
	v_and_b32_e32 v4, 31, v74
	v_lshlrev_b32_e32 v4, 2, v4
	v_lshrrev_b32_e32 v5, 3, v74
	v_and_b32_e32 v6, 7, v74
	v_mul_u32_u24_e32 v2, 264, v6
	v_add_u32_e32 v2, v2, v5
	v_lshl_add_u32 v2, v2, 2, v75
	v_lshlrev_b32_e32 v6, 4, v6
	v_mul_u32_u24_e32 v1, 132, v5
	v_add3_u32 v1, v1, v6, v75
	v_readfirstlane_b32 s13, v154
	s_lshr_b32 s13, s13, 6
	s_lshl_b32 s26, s96, 3
	s_add_u32 s13, s13, s26
	s_sub_u32 s12, s13, 1024
	s_add_u32 s12, s12, 44544
	s_waitcnt lgkmcnt(0)
	s_cmp_ge_u32 s12, 60928
	s_cbranch_scc1 .Ltrs_done
	s_cmp_ge_u32 s12, 33280
	s_cselect_b32 s41, 1, 0
	s_cselect_b32 s26, 33280, 0
	s_sub_u32 s42, s12, s26
	s_cmp_ge_u32 s42, 12288
	s_cbranch_scc1 .Ltrs_m2
	s_mul_i32 s43, s42, 43691
	s_lshr_b32 s43, s43, 24
	s_mul_i32 s26, s43, 384
	s_sub_u32 s44, s42, s26
	s_mov_b32 s14, s0
	s_mov_b32 s15, s1
	s_mov_b32 s36, 0xc000
	s_mov_b32 s37, 0x6000000
	s_mov_b32 s38, 0x0
	s_mov_b32 s39, 0x3000000
	s_mov_b32 s40, 0x1000
	s_branch .Ltrs_dec_done1

.Ltrs_loop:
	s_add_u32 s12, s12, 1024
	s_cmp_lt_u32 s12, 60928
	s_cselect_b32 s24, 1, 0
	s_cbranch_scc0 .Ltrs_nonext8
	s_cmp_ge_u32 s12, 33280
	s_cselect_b32 s41, 1, 0
	s_cselect_b32 s26, 33280, 0
	s_sub_u32 s42, s12, s26
	s_cmp_ge_u32 s42, 12288
	s_cbranch_scc1 .Ltrs_m11
	s_mul_i32 s43, s42, 43691
	s_lshr_b32 s43, s43, 24
	s_mul_i32 s26, s43, 384
	s_sub_u32 s44, s42, s26
	s_mov_b32 s16, s0
	s_mov_b32 s17, s1
	s_mov_b32 s36, 0xc000
	s_mov_b32 s37, 0x6000000
	s_mov_b32 s38, 0x0
	s_mov_b32 s39, 0x3000000
	s_mov_b32 s40, 0x1000
	s_branch .Ltrs_dec_done10

.Ltrs_after9:
	ds_write_b32 v1, v10 offset:0
	ds_write_b32 v1, v11 offset:4
	ds_write_b32 v1, v12 offset:8
	ds_write_b32 v1, v13 offset:12
	ds_write_b32 v1, v14 offset:1056
	ds_write_b32 v1, v15 offset:1060
	ds_write_b32 v1, v16 offset:1064
	ds_write_b32 v1, v17 offset:1068
	ds_write_b32 v1, v18 offset:2112
	ds_write_b32 v1, v19 offset:2116
	ds_write_b32 v1, v20 offset:2120
	ds_write_b32 v1, v21 offset:2124
	ds_write_b32 v1, v22 offset:3168
	ds_write_b32 v1, v23 offset:3172
	ds_write_b32 v1, v24 offset:3176
	ds_write_b32 v1, v25 offset:3180
	ds_write_b32 v1, v26 offset:4224
	ds_write_b32 v1, v27 offset:4228
	ds_write_b32 v1, v28 offset:4232
	ds_write_b32 v1, v29 offset:4236
	ds_write_b32 v1, v30 offset:5280
	ds_write_b32 v1, v31 offset:5284
	ds_write_b32 v1, v32 offset:5288
	ds_write_b32 v1, v33 offset:5292
	ds_write_b32 v1, v34 offset:6336
	ds_write_b32 v1, v35 offset:6340
	ds_write_b32 v1, v36 offset:6344
	ds_write_b32 v1, v37 offset:6348
	ds_write_b32 v1, v38 offset:7392
	ds_write_b32 v1, v39 offset:7396
	ds_write_b32 v1, v40 offset:7400
	ds_write_b32 v1, v41 offset:7404
	v_mad_u32_u24 v9, v5, s22, v6
	s_lshl_b32 s46, s22, 3
	s_waitcnt lgkmcnt(0)
	ds_read_b32 v74, v2 offset:0
	ds_read_b32 v75, v2 offset:132
	ds_read_b32 v76, v2 offset:264
	ds_read_b32 v77, v2 offset:396
	ds_read_b32 v78, v2 offset:528
	ds_read_b32 v79, v2 offset:660
	ds_read_b32 v80, v2 offset:792
	ds_read_b32 v81, v2 offset:924
	ds_read_b32 v82, v2 offset:32
	ds_read_b32 v83, v2 offset:164
	ds_read_b32 v84, v2 offset:296
	ds_read_b32 v85, v2 offset:428
	ds_read_b32 v86, v2 offset:560
	ds_read_b32 v87, v2 offset:692
	ds_read_b32 v88, v2 offset:824
	ds_read_b32 v89, v2 offset:956
	s_waitcnt lgkmcnt(8)
	v_cvt_pk_bf16_f32 v106, v74, v75
	v_cvt_pk_bf16_f32 v107, v76, v77
	v_cvt_pk_bf16_f32 v108, v78, v79
	v_cvt_pk_bf16_f32 v109, v80, v81
	global_store_dwordx4 v9, v[106:109], s[18:19]
	s_add_u32 s18, s18, s46
	s_addc_u32 s19, s19, 0
	ds_read_b32 v90, v2 offset:64
	ds_read_b32 v91, v2 offset:196
	ds_read_b32 v92, v2 offset:328
	ds_read_b32 v93, v2 offset:460
	ds_read_b32 v94, v2 offset:592
	ds_read_b32 v95, v2 offset:724
	ds_read_b32 v96, v2 offset:856
	ds_read_b32 v97, v2 offset:988
	s_waitcnt lgkmcnt(8)
	v_cvt_pk_bf16_f32 v110, v82, v83
	v_cvt_pk_bf16_f32 v111, v84, v85
	v_cvt_pk_bf16_f32 v112, v86, v87
	v_cvt_pk_bf16_f32 v113, v88, v89
	global_store_dwordx4 v9, v[110:113], s[18:19]
	s_add_u32 s18, s18, s46
	s_addc_u32 s19, s19, 0
	ds_read_b32 v98, v2 offset:96
	ds_read_b32 v99, v2 offset:228
	ds_read_b32 v100, v2 offset:360
	ds_read_b32 v101, v2 offset:492
	ds_read_b32 v102, v2 offset:624
	ds_read_b32 v103, v2 offset:756
	ds_read_b32 v104, v2 offset:888
	ds_read_b32 v105, v2 offset:1020
	s_waitcnt lgkmcnt(8)
	v_cvt_pk_bf16_f32 v106, v90, v91
	v_cvt_pk_bf16_f32 v107, v92, v93
	v_cvt_pk_bf16_f32 v108, v94, v95
	v_cvt_pk_bf16_f32 v109, v96, v97
	global_store_dwordx4 v9, v[106:109], s[18:19]
	s_add_u32 s18, s18, s46
	s_addc_u32 s19, s19, 0
	s_waitcnt lgkmcnt(0)
	v_cvt_pk_bf16_f32 v110, v98, v99
	v_cvt_pk_bf16_f32 v111, v100, v101
	v_cvt_pk_bf16_f32 v112, v102, v103
	v_cvt_pk_bf16_f32 v113, v104, v105
	global_store_dwordx4 v9, v[110:113], s[18:19]
	s_cmp_eq_u32 s24, 0
	s_cbranch_scc1 .Ltrs_done
	s_add_u32 s12, s12, 1024
	s_cmp_lt_u32 s12, 60928
	s_cselect_b32 s24, 1, 0
	s_cbranch_scc0 .Ltrs_nonext17
	s_cmp_ge_u32 s12, 33280
	s_cselect_b32 s41, 1, 0
	s_cselect_b32 s26, 33280, 0
	s_sub_u32 s42, s12, s26
	s_cmp_ge_u32 s42, 12288
	s_cbranch_scc1 .Ltrs_m20
	s_mul_i32 s43, s42, 43691
	s_lshr_b32 s43, s43, 24
	s_mul_i32 s26, s43, 384
	s_sub_u32 s44, s42, s26
	s_mov_b32 s14, s0
	s_mov_b32 s15, s1
	s_mov_b32 s36, 0xc000
	s_mov_b32 s37, 0x6000000
	s_mov_b32 s38, 0x0
	s_mov_b32 s39, 0x3000000
	s_mov_b32 s40, 0x1000
	s_branch .Ltrs_dec_done19

.LBB0_2416:
	s_waitcnt vmcnt(0)
	s_barrier
	s_cmp_lt_u32 s96, 128
	s_cbranch_scc1 .LBB0_2417
	s_load_dwordx2 s[0:1], s[92:93], 0x58
	s_load_dwordx2 s[2:3], s[92:93], 0xb8
	s_load_dwordx2 s[4:5], s[92:93], 0xc0
	s_load_dwordx2 s[6:7], s[92:93], 0xc8
	s_load_dwordx2 s[8:9], s[92:93], 0xd0
	s_load_dwordx2 s[10:11], s[92:93], 0xe8
	v_and_b32_e32 v74, 63, v154
	v_lshrrev_b32_e32 v75, 6, v154
	v_mul_u32_u24_e32 v75, 0x2100, v75
	v_lshrrev_b32_e32 v3, 5, v74
	v_and_b32_e32 v4, 31, v74
	v_lshlrev_b32_e32 v4, 2, v4
	v_lshrrev_b32_e32 v5, 3, v74
	v_and_b32_e32 v6, 7, v74
	v_mul_u32_u24_e32 v2, 264, v6
	v_add_u32_e32 v2, v2, v5
	v_lshl_add_u32 v2, v2, 2, v75
	v_lshlrev_b32_e32 v6, 4, v6
	v_mul_u32_u24_e32 v1, 132, v5
	v_add3_u32 v1, v1, v6, v75
	v_readfirstlane_b32 s13, v154
	s_lshr_b32 s13, s13, 6
	s_lshl_b32 s26, s96, 3
	s_add_u32 s13, s13, s26
	s_sub_u32 s12, s13, 1024
	s_add_u32 s12, s12, 60928
	s_waitcnt lgkmcnt(0)
	s_cmp_ge_u32 s12, 66560
	s_cbranch_scc1 .Ltrt_done
	s_cmp_ge_u32 s12, 33280
	s_cselect_b32 s41, 1, 0
	s_cselect_b32 s26, 33280, 0
	s_sub_u32 s42, s12, s26
	s_cmp_ge_u32 s42, 12288
	s_cbranch_scc1 .Ltrt_m2
	s_mul_i32 s43, s42, 43691
	s_lshr_b32 s43, s43, 24
	s_mul_i32 s26, s43, 384
	s_sub_u32 s44, s42, s26
	s_mov_b32 s14, s0
	s_mov_b32 s15, s1
	s_mov_b32 s36, 0xc000
	s_mov_b32 s37, 0x6000000
	s_mov_b32 s38, 0x0
	s_mov_b32 s39, 0x3000000
	s_mov_b32 s40, 0x1000
	s_branch .Ltrt_dec_done1

.Ltrt_done:
	s_waitcnt vmcnt(0) lgkmcnt(0)
	s_branch .LBB0_2417
.LBB0_2417:
	s_cmp_gt_i32 s87, 19
	s_cbranch_scc1 .LBB0_2563
	s_load_dword s0, s[92:93], 0x104
	s_waitcnt lgkmcnt(0)
	s_cmp_lt_i32 s0, 20
	s_cbranch_scc1 .LBB0_2563
	s_cmp_eq_u32 s87, 19
	s_cbranch_scc1 .LBB0_2487
	s_cmp_lt_u32 s0, 23
	s_mov_b64 s[0:1], -1
	s_cbranch_scc0 .LBB0_2474
	s_getreg_b32 s2, hwreg(HW_REG_XCC_ID, 0, 4)
	s_waitcnt vmcnt(0)
	s_waitcnt vmcnt(0)
	s_barrier
	s_mov_b64 s[0:1], exec
	v_readlane_b32 s4, v232, 4
	v_readlane_b32 s5, v232, 5
	s_and_b64 s[4:5], s[0:1], s[4:5]
	s_mov_b64 exec, s[4:5]
	s_cbranch_execz .LBB0_2473
	s_add_i32 s3, 0, 0x20000
	v_mov_b32_e32 v1, s3
	s_waitcnt vmcnt(0) expcnt(0) lgkmcnt(0)
	ds_read_b32 v3, v1
	s_add_i32 s3, 0, 0x20004
	v_mov_b32_e32 v1, s3
	ds_read_b32 v1, v1
	s_and_b32 s33, s2, 15
	s_waitcnt lgkmcnt(1)
	v_cmp_ne_u32_e32 vcc, 0, v3
	s_cbranch_vccnz .LBB0_2437
	s_add_u32 s2, s90, 0x2c918200
	s_addc_u32 s3, s91, 0
	s_add_u32 s4, s90, 0x2c918400
	s_addc_u32 s5, s91, 0
	s_add_u32 s6, s90, 0x2c918500
	s_addc_u32 s7, s91, 0
	s_add_u32 s8, s90, 0x2c918600
	s_addc_u32 s9, s91, 0
	s_add_u32 s10, s90, 0x2c918700
	s_addc_u32 s11, s91, 0
	s_add_u32 s12, s90, 0x2c918800
	s_addc_u32 s13, s91, 0
	s_add_u32 s14, s90, 0x2c918900
	s_addc_u32 s15, s91, 0
	s_add_u32 s16, s90, 0x2c918a00
	s_addc_u32 s17, s91, 0
	s_add_u32 s18, s90, 0x2c918b00
	s_addc_u32 s19, s91, 0
	s_add_u32 s20, s90, 0x2c918c00
	s_addc_u32 s21, s91, 0
	s_add_u32 s22, s90, 0x2c918d00
	s_addc_u32 s23, s91, 0
	s_add_u32 s24, s90, 0x2c918e00
	s_addc_u32 s25, s91, 0
	s_add_u32 s26, s90, 0x2c918f00
	s_addc_u32 s27, s91, 0
	s_add_u32 s28, s90, 0x2c919000
	s_addc_u32 s29, s91, 0
	s_add_u32 s30, s90, 0x2c919100
	s_addc_u32 s31, s91, 0
	s_add_u32 s34, s90, 0x2c919200
	s_addc_u32 s35, s91, 0
	s_mul_i32 s44, s95, s97
	s_add_u32 s36, s90, 0x2c919300
	s_mul_i32 s44, s44, s94
	s_addc_u32 s37, s91, 0
	s_mov_b32 s45, 1
	v_mov_b32_e32 v17, 0
	s_branch .LBB0_2425
